# burst QK ds_reads (B loop, C pair loop) + short sleep for waves 0-3 before A-loop QK
# speedup vs baseline: 1.0054x; 1.0054x over previous
.LBB0_164:
	s_add_i32 s20, s6, -1
	s_cmp_le_i32 s20, s3
	s_cselect_b64 s[22:23], -1, 0
	s_cmp_gt_i32 s6, s19
	s_cselect_b64 s[24:25], -1, 0
	s_and_b64 s[22:23], s[22:23], s[24:25]
	s_andn2_b64 vcc, exec, s[22:23]
	s_cbranch_vccnz .LBB0_162
	s_and_b32 s21, s20, 3
	s_mul_i32 s7, s21, 0x2400
	v_add_u32_e32 v0, s7, v139
	ds_read_b128 v[2:5], v0
	ds_read_b128 v[208:211], v0 offset:4608
	ds_read_b128 v[212:215], v0 offset:32
	ds_read_b128 v[216:219], v0 offset:4640
	ds_read_b128 v[220:223], v0 offset:64
	ds_read_b128 v[224:227], v0 offset:4672
	ds_read_b128 v[228:231], v0 offset:96
	ds_read_b128 v[232:235], v0 offset:4704
	s_cmp_lt_i32 s6, 33
	s_cselect_b64 s[6:7], -1, 0
	s_and_b64 vcc, exec, s[6:7]
	s_waitcnt lgkmcnt(7)
	v_mfma_f32_32x32x16_bf16 v[48:63], v[2:5], v[96:99], 0
	s_waitcnt lgkmcnt(6)
	v_mfma_f32_32x32x16_bf16 v[64:79], v[208:211], v[96:99], 0
	s_waitcnt lgkmcnt(5)
	v_mfma_f32_32x32x16_bf16 v[48:63], v[212:215], v[100:103], v[48:63]
	s_waitcnt lgkmcnt(4)
	v_mfma_f32_32x32x16_bf16 v[64:79], v[216:219], v[100:103], v[64:79]
	s_waitcnt lgkmcnt(3)
	v_mfma_f32_32x32x16_bf16 v[48:63], v[220:223], v[104:107], v[48:63]
	s_waitcnt lgkmcnt(2)
	v_mfma_f32_32x32x16_bf16 v[64:79], v[224:227], v[104:107], v[64:79]
	s_waitcnt lgkmcnt(1)
	v_mfma_f32_32x32x16_bf16 v[48:63], v[228:231], v[108:111], v[48:63]
	s_waitcnt lgkmcnt(0)
	v_mfma_f32_32x32x16_bf16 v[64:79], v[232:235], v[108:111], v[64:79]
	s_cbranch_vccnz .LBB0_167
	s_nop 10
	v_mov_b32_e32 v64, 0xff800000
	v_mov_b32_e32 v65, v64
	v_mov_b32_e32 v14, v64
	v_mov_b32_e32 v15, v64
	v_mov_b32_e32 v12, v64
	v_mov_b32_e32 v13, v64
	v_mov_b32_e32 v10, v64
	v_mov_b32_e32 v11, v64
	v_mov_b32_e32 v8, v64
	v_mov_b32_e32 v9, v64
	v_mov_b32_e32 v6, v64
	v_mov_b32_e32 v7, v64
	v_mov_b32_e32 v4, v64
	v_mov_b32_e32 v5, v64
	v_mov_b32_e32 v2, v64
	v_mov_b32_e32 v3, v64
	s_branch .LBB0_168

.LBB0_657:
	s_andn2_b64 vcc, exec, s[0:1]
	s_mov_b64 s[16:17], -1
	s_cbranch_vccnz .LBB0_668
	s_add_i32 s51, s13, s23
	s_sub_i32 s0, s51, 64
	s_cmp_ge_i32 s0, s53
	s_mov_b64 s[16:17], 0
	s_cbranch_scc1 .LBB0_668
	v_add3_u32 v0, s28, v209, v210
	ds_read_b128 v[2:5], v0
	ds_read_b128 v[184:187], v0 offset:4608
	ds_read_b128 v[188:191], v0 offset:32
	ds_read_b128 v[224:227], v0 offset:4640
	ds_read_b128 v[228:231], v0 offset:64
	ds_read_b128 v[232:235], v0 offset:4672
	ds_read_b128 v[236:239], v0 offset:96
	ds_read_b128 v[240:243], v0 offset:4704
	s_sub_i32 s0, s51, 63
	s_cmp_lt_i32 s0, s20
	s_cselect_b64 s[62:63], -1, 0
	s_cmp_ge_i32 s0, s20
	v_mov_b32_e32 v15, 0
	s_waitcnt lgkmcnt(7)
	v_mfma_f32_32x32x16_bf16 v[48:63], v[2:5], v[96:99], 0
	s_waitcnt lgkmcnt(6)
	v_mfma_f32_32x32x16_bf16 v[64:79], v[184:187], v[96:99], 0
	s_waitcnt lgkmcnt(5)
	v_mfma_f32_32x32x16_bf16 v[48:63], v[188:191], v[100:103], v[48:63]
	s_waitcnt lgkmcnt(4)
	v_mfma_f32_32x32x16_bf16 v[64:79], v[224:227], v[100:103], v[64:79]
	s_waitcnt lgkmcnt(3)
	v_mfma_f32_32x32x16_bf16 v[48:63], v[228:231], v[104:107], v[48:63]
	s_waitcnt lgkmcnt(2)
	v_mfma_f32_32x32x16_bf16 v[64:79], v[232:235], v[104:107], v[64:79]
	s_waitcnt lgkmcnt(1)
	v_mfma_f32_32x32x16_bf16 v[48:63], v[236:239], v[108:111], v[48:63]
	s_waitcnt lgkmcnt(0)
	v_mfma_f32_32x32x16_bf16 v[64:79], v[240:243], v[108:111], v[64:79]
	s_cbranch_scc1 .LBB0_663
	s_nop 10
	v_mul_f32_e32 v0, 0x3fb8aa3b, v64
	v_min_f32_e32 v0, 0x42a00000, v0
	v_exp_f32_e32 v2, v0
	v_mul_f32_e32 v0, 0x3fb8aa3b, v65
	v_min_f32_e32 v0, 0x42a00000, v0
	v_exp_f32_e32 v3, v0
	v_add_f32_e32 v0, 1.0, v2
	v_rcp_f32_e32 v6, v0
	v_mul_f32_e32 v5, 0x3fb8aa3b, v67
	v_add_f32_e32 v0, 1.0, v3
	v_mul_f32_e32 v10, 0x3fb8aa3b, v69
	v_rcp_f32_e32 v7, v0
	v_mul_f32_e32 v0, 0x3fb8aa3b, v66
	v_min_f32_e32 v5, 0x42a00000, v5
	v_min_f32_e32 v10, 0x42a00000, v10
	v_min_f32_e32 v0, 0x42a00000, v0
	v_exp_f32_e32 v8, v5
	v_mul_f32_e32 v5, 0x3fb8aa3b, v68
	v_exp_f32_e32 v12, v10
	v_mul_f32_e32 v10, 0x3fb8aa3b, v70
	v_exp_f32_e32 v0, v0
	v_min_f32_e32 v5, 0x42a00000, v5
	v_min_f32_e32 v10, 0x42a00000, v10
	v_exp_f32_e32 v9, v5
	v_exp_f32_e32 v13, v10
	v_add_f32_e32 v4, 1.0, v0
	v_add_f32_e32 v10, 1.0, v12
	v_rcp_f32_e32 v180, v4
	v_add_f32_e32 v4, 1.0, v8
	v_add_f32_e32 v5, 1.0, v9
	v_rcp_f32_e32 v66, v10
	v_add_f32_e32 v10, 1.0, v13
	v_rcp_f32_e32 v4, v4
	v_rcp_f32_e32 v5, v5
	v_rcp_f32_e32 v67, v10
	v_mul_f32_e32 v10, 0x3fb8aa3b, v71
	v_min_f32_e32 v10, 0x42a00000, v10
	v_exp_f32_e32 v65, v10
	v_pk_mul_f32 v[10:11], v[8:9], v[4:5]
	v_pk_mul_f32 v[8:9], v[12:13], v[66:67]
	v_mul_f32_e32 v13, 0x3fb8aa3b, v72
	v_min_f32_e32 v13, 0x42a00000, v13
	v_exp_f32_e32 v14, v13
	v_mul_f32_e32 v13, 0x3fb8aa3b, v73
	v_min_f32_e32 v13, 0x42a00000, v13
	v_exp_f32_e32 v15, v13
	v_add_f32_e32 v12, 1.0, v65
	v_rcp_f32_e32 v13, v12
	v_add_f32_e32 v12, 1.0, v14
	v_rcp_f32_e32 v64, v12
	v_add_f32_e32 v12, 1.0, v15
	v_rcp_f32_e32 v68, v12
	v_mul_f32_e32 v12, 0x3fb8aa3b, v74
	v_min_f32_e32 v12, 0x42a00000, v12
	v_exp_f32_e32 v12, v12
	v_mul_f32_e32 v181, v65, v13
	v_mov_b32_e32 v65, v68
	v_pk_mul_f32 v[14:15], v[14:15], v[64:65]
	v_add_f32_e32 v65, 1.0, v12
	v_rcp_f32_e32 v70, v65
	v_mul_f32_e32 v65, 0x3fb8aa3b, v75
	v_min_f32_e32 v65, 0x42a00000, v65
	v_exp_f32_e32 v72, v65
	v_mul_f32_e32 v65, 0x3fb8aa3b, v76
	v_min_f32_e32 v65, 0x42a00000, v65
	v_exp_f32_e32 v73, v65
	v_mul_f32_e32 v182, v12, v70
	v_add_f32_e32 v12, 1.0, v72
	v_rcp_f32_e32 v74, v12
	v_add_f32_e32 v12, 1.0, v73
	v_rcp_f32_e32 v65, v12
	v_mul_f32_e32 v12, 0x3fb8aa3b, v77
	v_min_f32_e32 v12, 0x42a00000, v12
	v_exp_f32_e32 v76, v12
	v_mul_f32_e32 v12, 0x3fb8aa3b, v78
	v_min_f32_e32 v12, 0x42a00000, v12
	v_exp_f32_e32 v77, v12
	v_add_f32_e32 v12, 1.0, v76
	v_rcp_f32_e32 v69, v12
	v_mov_b32_e32 v75, v65
	v_add_f32_e32 v12, 1.0, v77
	v_rcp_f32_e32 v71, v12
	v_mul_f32_e32 v12, 0x3fb8aa3b, v79
	v_min_f32_e32 v12, 0x42a00000, v12
	v_exp_f32_e32 v12, v12
	v_pk_mul_f32 v[78:79], v[72:73], v[74:75]
	v_mov_b32_e32 v72, v69
	v_mov_b32_e32 v73, v71
	v_add_f32_e32 v75, 1.0, v12
	v_rcp_f32_e32 v75, v75
	s_add_i32 s0, s51, -1
	v_pk_mul_f32 v[2:3], v[2:3], v[6:7]
	v_mul_f32_e32 v0, v0, v180
	v_pk_mul_f32 v[76:77], v[76:77], v[72:73]
	s_cmp_lt_i32 s0, s20
	v_mul_f32_e32 v183, v12, v75
	s_cbranch_scc1 .LBB0_662
	v_add3_u32 v12, s21, v151, 64
	v_cmp_lt_i32_e32 vcc, 0, v12
	v_cmp_lt_i32_e64 s[0:1], 1, v12
	v_cmp_lt_i32_e64 s[18:19], 24, v12
	v_cndmask_b32_e32 v6, 1.0, v6, vcc
	v_cndmask_b32_e32 v2, 0, v2, vcc
	v_cmp_lt_i32_e32 vcc, 2, v12
	v_cndmask_b32_e64 v7, 1.0, v7, s[0:1]
	v_cndmask_b32_e64 v3, 0, v3, s[0:1]
	v_cndmask_b32_e32 v180, 1.0, v180, vcc
	v_cndmask_b32_e32 v0, 0, v0, vcc
	v_cmp_lt_i32_e32 vcc, 3, v12
	v_cmp_lt_i32_e64 s[0:1], 8, v12
	v_cmp_lt_i32_e64 s[16:17], 18, v12
	v_cndmask_b32_e32 v4, 1.0, v4, vcc
	v_cndmask_b32_e32 v10, 0, v10, vcc
	v_cmp_lt_i32_e32 vcc, 9, v12
	v_cndmask_b32_e64 v5, 1.0, v5, s[0:1]
	v_cndmask_b32_e64 v11, 0, v11, s[0:1]
	v_cndmask_b32_e32 v66, 1.0, v66, vcc
	v_cndmask_b32_e32 v8, 0, v8, vcc
	v_cmp_lt_i32_e32 vcc, 11, v12
	v_cmp_lt_i32_e64 s[0:1], 10, v12
	v_cndmask_b32_e64 v65, 1.0, v65, s[18:19]
	v_cndmask_b32_e32 v13, 1.0, v13, vcc
	v_cndmask_b32_e32 v181, 0, v181, vcc
	v_cmp_lt_i32_e32 vcc, 17, v12
	v_cndmask_b32_e64 v67, 1.0, v67, s[0:1]
	v_cndmask_b32_e64 v9, 0, v9, s[0:1]
	v_cndmask_b32_e32 v15, 0, v15, vcc
	v_cmp_lt_i32_e64 s[0:1], 16, v12
	v_cndmask_b32_e32 v68, 1.0, v68, vcc
	v_cmp_lt_i32_e32 vcc, 26, v12
	v_cndmask_b32_e64 v14, 0, v14, s[0:1]
	v_cndmask_b32_e64 v64, 1.0, v64, s[0:1]
	v_cndmask_b32_e64 v79, 0, v79, s[18:19]
	v_cmp_lt_i32_e64 s[0:1], 19, v12
	v_cmp_lt_i32_e64 s[18:19], 25, v12
	v_cndmask_b32_e32 v71, 1.0, v71, vcc
	v_cndmask_b32_e32 v77, 0, v77, vcc
	v_cmp_lt_i32_e32 vcc, 27, v12
	v_cndmask_b32_e64 v182, 0, v182, s[16:17]
	v_cndmask_b32_e64 v78, 0, v78, s[0:1]
	v_cndmask_b32_e64 v69, 1.0, v69, s[18:19]
	v_cndmask_b32_e64 v70, 1.0, v70, s[16:17]
	v_cndmask_b32_e64 v76, 0, v76, s[18:19]
	v_cndmask_b32_e32 v75, 1.0, v75, vcc
	v_cndmask_b32_e64 v74, 1.0, v74, s[0:1]
	v_cndmask_b32_e32 v183, 0, v183, vcc

.LBB0_668:
	s_cmp_gt_i32 s25, s8
	s_cselect_b64 s[0:1], -1, 0
	s_and_b64 s[0:1], s[0:1], s[42:43]
	s_andn2_b64 vcc, exec, s[0:1]
	s_cbranch_vccnz .LBB0_675
	s_xor_b64 s[0:1], s[16:17], -1
	s_andn2_b64 vcc, exec, s[0:1]
	s_mov_b64 s[16:17], -1
	s_cbranch_vccnz .LBB0_675
	s_add_i32 s25, s13, s23
	s_add_i32 s0, s25, 0xffffff80
	s_cmp_ge_i32 s0, s53
	s_mov_b64 s[16:17], 0
	s_cbranch_scc1 .LBB0_675
	v_add3_u32 v0, s26, v209, v210
	ds_read_b128 v[2:5], v0
	ds_read_b128 v[184:187], v0 offset:4608
	ds_read_b128 v[188:191], v0 offset:32
	ds_read_b128 v[224:227], v0 offset:4640
	ds_read_b128 v[228:231], v0 offset:64
	ds_read_b128 v[232:235], v0 offset:4672
	ds_read_b128 v[236:239], v0 offset:96
	ds_read_b128 v[240:243], v0 offset:4704
	s_add_i32 s0, s25, 0xffffff81
	s_cmp_lt_i32 s0, s20
	s_cselect_b64 s[62:63], -1, 0
	s_cmp_ge_i32 s0, s20
	v_mov_b32_e32 v15, 0
	s_waitcnt lgkmcnt(7)
	v_mfma_f32_32x32x16_bf16 v[48:63], v[2:5], v[96:99], 0
	s_waitcnt lgkmcnt(6)
	v_mfma_f32_32x32x16_bf16 v[64:79], v[184:187], v[96:99], 0
	s_waitcnt lgkmcnt(5)
	v_mfma_f32_32x32x16_bf16 v[48:63], v[188:191], v[100:103], v[48:63]
	s_waitcnt lgkmcnt(4)
	v_mfma_f32_32x32x16_bf16 v[64:79], v[224:227], v[100:103], v[64:79]
	s_waitcnt lgkmcnt(3)
	v_mfma_f32_32x32x16_bf16 v[48:63], v[228:231], v[104:107], v[48:63]
	s_waitcnt lgkmcnt(2)
	v_mfma_f32_32x32x16_bf16 v[64:79], v[232:235], v[104:107], v[64:79]
	s_waitcnt lgkmcnt(1)
	v_mfma_f32_32x32x16_bf16 v[48:63], v[236:239], v[108:111], v[48:63]
	s_waitcnt lgkmcnt(0)
	v_mfma_f32_32x32x16_bf16 v[64:79], v[240:243], v[108:111], v[64:79]
	s_cbranch_scc1 .LBB0_677
	s_nop 10
	v_mul_f32_e32 v0, 0x3fb8aa3b, v64
	v_min_f32_e32 v0, 0x42a00000, v0
	v_exp_f32_e32 v2, v0
	v_mul_f32_e32 v0, 0x3fb8aa3b, v65
	v_min_f32_e32 v0, 0x42a00000, v0
	v_exp_f32_e32 v3, v0
	v_add_f32_e32 v0, 1.0, v2
	v_rcp_f32_e32 v6, v0
	v_mul_f32_e32 v5, 0x3fb8aa3b, v67
	v_add_f32_e32 v0, 1.0, v3
	v_mul_f32_e32 v10, 0x3fb8aa3b, v69
	v_rcp_f32_e32 v7, v0
	v_mul_f32_e32 v0, 0x3fb8aa3b, v66
	v_min_f32_e32 v5, 0x42a00000, v5
	v_min_f32_e32 v10, 0x42a00000, v10
	v_min_f32_e32 v0, 0x42a00000, v0
	v_exp_f32_e32 v8, v5
	v_mul_f32_e32 v5, 0x3fb8aa3b, v68
	v_exp_f32_e32 v12, v10
	v_mul_f32_e32 v10, 0x3fb8aa3b, v70
	v_exp_f32_e32 v0, v0
	v_min_f32_e32 v5, 0x42a00000, v5
	v_min_f32_e32 v10, 0x42a00000, v10
	v_exp_f32_e32 v9, v5
	v_exp_f32_e32 v13, v10
	v_add_f32_e32 v4, 1.0, v0
	v_add_f32_e32 v10, 1.0, v12
	v_rcp_f32_e32 v180, v4
	v_add_f32_e32 v4, 1.0, v8
	v_add_f32_e32 v5, 1.0, v9
	v_rcp_f32_e32 v66, v10
	v_add_f32_e32 v10, 1.0, v13
	v_rcp_f32_e32 v4, v4
	v_rcp_f32_e32 v5, v5
	v_rcp_f32_e32 v67, v10
	v_mul_f32_e32 v10, 0x3fb8aa3b, v71
	v_min_f32_e32 v10, 0x42a00000, v10
	v_exp_f32_e32 v65, v10
	v_pk_mul_f32 v[10:11], v[8:9], v[4:5]
	v_pk_mul_f32 v[8:9], v[12:13], v[66:67]
	v_mul_f32_e32 v13, 0x3fb8aa3b, v72
	v_min_f32_e32 v13, 0x42a00000, v13
	v_exp_f32_e32 v14, v13
	v_mul_f32_e32 v13, 0x3fb8aa3b, v73
	v_min_f32_e32 v13, 0x42a00000, v13
	v_exp_f32_e32 v15, v13
	v_add_f32_e32 v12, 1.0, v65
	v_rcp_f32_e32 v13, v12
	v_add_f32_e32 v12, 1.0, v14
	v_rcp_f32_e32 v64, v12
	v_add_f32_e32 v12, 1.0, v15
	v_rcp_f32_e32 v68, v12
	v_mul_f32_e32 v12, 0x3fb8aa3b, v74
	v_min_f32_e32 v12, 0x42a00000, v12
	v_exp_f32_e32 v12, v12
	v_mul_f32_e32 v181, v65, v13
	v_mov_b32_e32 v65, v68
	v_pk_mul_f32 v[14:15], v[14:15], v[64:65]
	v_add_f32_e32 v65, 1.0, v12
	v_rcp_f32_e32 v70, v65
	v_mul_f32_e32 v65, 0x3fb8aa3b, v75
	v_min_f32_e32 v65, 0x42a00000, v65
	v_exp_f32_e32 v72, v65
	v_mul_f32_e32 v65, 0x3fb8aa3b, v76
	v_min_f32_e32 v65, 0x42a00000, v65
	v_exp_f32_e32 v73, v65
	v_mul_f32_e32 v182, v12, v70
	v_add_f32_e32 v12, 1.0, v72
	v_rcp_f32_e32 v74, v12
	v_add_f32_e32 v12, 1.0, v73
	v_rcp_f32_e32 v65, v12
	v_mul_f32_e32 v12, 0x3fb8aa3b, v77
	v_min_f32_e32 v12, 0x42a00000, v12
	v_exp_f32_e32 v76, v12
	v_mul_f32_e32 v12, 0x3fb8aa3b, v78
	v_min_f32_e32 v12, 0x42a00000, v12
	v_exp_f32_e32 v77, v12
	v_add_f32_e32 v12, 1.0, v76
	v_rcp_f32_e32 v69, v12
	v_mov_b32_e32 v75, v65
	v_add_f32_e32 v12, 1.0, v77
	v_rcp_f32_e32 v71, v12
	v_mul_f32_e32 v12, 0x3fb8aa3b, v79
	v_min_f32_e32 v12, 0x42a00000, v12
	v_exp_f32_e32 v12, v12
	v_pk_mul_f32 v[78:79], v[72:73], v[74:75]
	v_mov_b32_e32 v72, v69
	v_mov_b32_e32 v73, v71
	v_add_f32_e32 v75, 1.0, v12
	v_rcp_f32_e32 v75, v75
	s_add_i32 s0, s25, 0xffffffbf
	v_pk_mul_f32 v[2:3], v[2:3], v[6:7]
	v_mul_f32_e32 v0, v0, v180
	v_pk_mul_f32 v[76:77], v[76:77], v[72:73]
	s_cmp_lt_i32 s0, s20
	v_mul_f32_e32 v183, v12, v75
	s_cbranch_scc1 .LBB0_674
	v_add_u32_e32 v12, s21, v151
	v_add_u32_e32 v12, 0x80, v12
	v_cmp_lt_i32_e32 vcc, 0, v12
	v_cmp_lt_i32_e64 s[0:1], 1, v12
	v_cmp_lt_i32_e64 s[18:19], 24, v12
	v_cndmask_b32_e32 v6, 1.0, v6, vcc
	v_cndmask_b32_e32 v2, 0, v2, vcc
	v_cmp_lt_i32_e32 vcc, 2, v12
	v_cndmask_b32_e64 v7, 1.0, v7, s[0:1]
	v_cndmask_b32_e64 v3, 0, v3, s[0:1]
	v_cndmask_b32_e32 v180, 1.0, v180, vcc
	v_cndmask_b32_e32 v0, 0, v0, vcc
	v_cmp_lt_i32_e32 vcc, 3, v12
	v_cmp_lt_i32_e64 s[0:1], 8, v12
	v_cmp_lt_i32_e64 s[16:17], 18, v12
	v_cndmask_b32_e32 v4, 1.0, v4, vcc
	v_cndmask_b32_e32 v10, 0, v10, vcc
	v_cmp_lt_i32_e32 vcc, 9, v12
	v_cndmask_b32_e64 v5, 1.0, v5, s[0:1]
	v_cndmask_b32_e64 v11, 0, v11, s[0:1]
	v_cndmask_b32_e32 v66, 1.0, v66, vcc
	v_cndmask_b32_e32 v8, 0, v8, vcc
	v_cmp_lt_i32_e32 vcc, 11, v12
	v_cmp_lt_i32_e64 s[0:1], 10, v12
	v_cndmask_b32_e64 v65, 1.0, v65, s[18:19]
	v_cndmask_b32_e32 v13, 1.0, v13, vcc
	v_cndmask_b32_e32 v181, 0, v181, vcc
	v_cmp_lt_i32_e32 vcc, 17, v12
	v_cndmask_b32_e64 v67, 1.0, v67, s[0:1]
	v_cndmask_b32_e64 v9, 0, v9, s[0:1]
	v_cndmask_b32_e32 v15, 0, v15, vcc
	v_cmp_lt_i32_e64 s[0:1], 16, v12
	v_cndmask_b32_e32 v68, 1.0, v68, vcc
	v_cmp_lt_i32_e32 vcc, 26, v12
	v_cndmask_b32_e64 v14, 0, v14, s[0:1]
	v_cndmask_b32_e64 v64, 1.0, v64, s[0:1]
	v_cndmask_b32_e64 v79, 0, v79, s[18:19]
	v_cmp_lt_i32_e64 s[0:1], 19, v12
	v_cmp_lt_i32_e64 s[18:19], 25, v12
	v_cndmask_b32_e32 v71, 1.0, v71, vcc
	v_cndmask_b32_e32 v77, 0, v77, vcc
	v_cmp_lt_i32_e32 vcc, 27, v12
	v_cndmask_b32_e64 v182, 0, v182, s[16:17]
	v_cndmask_b32_e64 v78, 0, v78, s[0:1]
	v_cndmask_b32_e64 v69, 1.0, v69, s[18:19]
	v_cndmask_b32_e64 v70, 1.0, v70, s[16:17]
	v_cndmask_b32_e64 v76, 0, v76, s[18:19]
	v_cndmask_b32_e32 v75, 1.0, v75, vcc
	v_cndmask_b32_e64 v74, 1.0, v74, s[0:1]
	v_cndmask_b32_e32 v183, 0, v183, vcc

.LBB0_778:
	s_add_i32 s16, s4, s2
	s_add_i32 s17, s16, 0xffffff40
	s_lshr_b32 s17, s17, 6
	s_cmp_le_i32 s17, s40
	s_cselect_b64 s[18:19], -1, 0
	s_cmp_ge_i32 s17, s41
	s_cselect_b64 s[26:27], -1, 0
	s_and_b64 s[18:19], s[18:19], s[26:27]
	s_andn2_b64 vcc, exec, s[18:19]
	s_cbranch_vccnz .LBB0_790
	v_cmp_gt_u32_e32 vcc, 0x100, v144
	s_cbranch_vccz .Lmy_sk1
	s_sleep 2
.Lmy_sk1:
	v_add3_u32 v0, s24, v209, v210
	ds_read_b128 v[2:5], v0 offset:4608
	ds_read_b128 v[6:9], v0
	ds_read_b128 v[10:13], v0 offset:32
	ds_read_b128 v[176:179], v0 offset:4640
	ds_read_b128 v[180:183], v0 offset:64
	ds_read_b128 v[184:187], v0 offset:4672
	ds_read_b128 v[188:191], v0 offset:96
	ds_read_b128 v[228:231], v0 offset:4704
	s_waitcnt lgkmcnt(6)
	v_mfma_f32_32x32x16_bf16 v[64:79], v[6:9], v[96:99], 0
	s_add_i32 s18, s16, -1
	s_mov_b64 s[16:17], -1
	s_cmp_gt_i32 s18, s20
	v_mfma_f32_32x32x16_bf16 v[48:63], v[2:5], v[96:99], 0
	s_waitcnt lgkmcnt(5)
	v_mfma_f32_32x32x16_bf16 v[64:79], v[10:13], v[100:103], v[64:79]
	s_waitcnt lgkmcnt(4)
	v_mfma_f32_32x32x16_bf16 v[48:63], v[176:179], v[100:103], v[48:63]
	s_waitcnt lgkmcnt(3)
	v_mfma_f32_32x32x16_bf16 v[64:79], v[180:183], v[104:107], v[64:79]
	s_waitcnt lgkmcnt(2)
	v_mfma_f32_32x32x16_bf16 v[48:63], v[184:187], v[104:107], v[48:63]
	s_waitcnt lgkmcnt(1)
	v_mfma_f32_32x32x16_bf16 v[64:79], v[188:191], v[108:111], v[64:79]
	s_waitcnt lgkmcnt(0)
	v_mfma_f32_32x32x16_bf16 v[48:63], v[228:231], v[108:111], v[48:63]
	s_cbranch_scc1 .LBB0_781
	v_mov_b32_e32 v0, s29
	ds_read_b32 v0, v0
	s_mov_b64 s[16:17], 0
	s_waitcnt lgkmcnt(0)
	s_nop 4
	v_pk_fma_f32 v[2:3], v[64:65], s[68:69], v[0:1] op_sel_hi:[1,0,0]
	s_nop 0
	v_pk_fma_f32 v[4:5], v[48:49], s[68:69], v[0:1] op_sel_hi:[1,0,0]
	v_pk_fma_f32 v[6:7], v[66:67], s[68:69], v[0:1] op_sel_hi:[1,0,0]
	v_pk_fma_f32 v[8:9], v[50:51], s[68:69], v[0:1] op_sel_hi:[1,0,0]
	v_pk_fma_f32 v[10:11], v[68:69], s[68:69], v[0:1] op_sel_hi:[1,0,0]
	v_pk_fma_f32 v[12:13], v[52:53], s[68:69], v[0:1] op_sel_hi:[1,0,0]
	v_pk_fma_f32 v[14:15], v[70:71], s[68:69], v[0:1] op_sel_hi:[1,0,0]
	v_pk_fma_f32 v[176:177], v[54:55], s[68:69], v[0:1] op_sel_hi:[1,0,0]
	v_pk_fma_f32 v[178:179], v[72:73], s[68:69], v[0:1] op_sel_hi:[1,0,0]
	v_pk_fma_f32 v[180:181], v[56:57], s[68:69], v[0:1] op_sel_hi:[1,0,0]
	v_pk_fma_f32 v[182:183], v[74:75], s[68:69], v[0:1] op_sel_hi:[1,0,0]
	v_pk_fma_f32 v[184:185], v[58:59], s[68:69], v[0:1] op_sel_hi:[1,0,0]
	v_pk_fma_f32 v[186:187], v[76:77], s[68:69], v[0:1] op_sel_hi:[1,0,0]
	v_pk_fma_f32 v[188:189], v[60:61], s[68:69], v[0:1] op_sel_hi:[1,0,0]
	v_pk_fma_f32 v[190:191], v[78:79], s[68:69], v[0:1] op_sel_hi:[1,0,0]
	v_pk_fma_f32 v[192:193], v[62:63], s[68:69], v[0:1] op_sel_hi:[1,0,0]
